# B28+rows7+rows10 + reversed workgroup index for the PLE GEMM in P3b (3-sample WGs get 3 PLE units, pool WGs 4)
# baseline (speedup 1.0000x reference)
.LBB0_961:
	s_cmpk_gt_i32 s66, 0x29f
	v_mbcnt_lo_u32_b32 v8, -1, 0
	v_mbcnt_hi_u32_b32 v8, -1, v8
	s_nop 0
	s_cbranch_scc1 .LBB0_978
	s_mov_b32 s99, s40
	s_sub_i32 s40, s7, s40
	s_sub_i32 s40, s40, 1
	v_lshl_add_u32 v0, v8, 4, s93
	v_add_u32_e32 v1, 0x2000, v0
	v_ashrrev_i32_e32 v2, 31, v1
	v_lshrrev_b32_e32 v2, 22, v2
	v_add_u32_e32 v2, v1, v2
	v_ashrrev_i32_e32 v2, 10, v2
	v_mul_i32_i24_e32 v3, 0x400, v2
	v_sub_u32_e32 v1, v1, v3
	v_lshrrev_b32_e32 v3, 4, v1
	v_bitop3_b32 v1, v3, v1, 32 bitop3:0x6c
	v_ashrrev_i32_e32 v3, 31, v1
	v_lshrrev_b32_e32 v3, 26, v3
	v_add_u32_e32 v3, v1, v3
	v_ashrrev_i32_e32 v4, 6, v3
	v_and_b32_e32 v3, 0xffc0, v3
	v_sub_u32_e32 v1, v1, v3
	v_lshlrev_b32_e32 v5, 3, v2
	v_lshrrev_b16_e32 v3, 7, v1
	v_and_b32_e32 v5, -16, v5
	v_and_b32_e32 v3, 1, v3
	v_add_u32_e32 v5, v4, v5
	v_add_u16_e32 v1, v1, v3
	v_mov_b32_e32 v3, 1
	v_and_b32_e32 v4, 3, v4
	s_mov_b32 s10, 0x7fffe0
	v_lshrrev_b32_e32 v6, 2, v5
	v_lshlrev_b32_e32 v7, 1, v5
	v_lshlrev_b32_e32 v2, 5, v2
	v_ashrrev_i16_sdwa v1, v3, sext(v1) dst_sel:DWORD dst_unused:UNUSED_PAD src0_sel:DWORD src1_sel:BYTE_0
	v_and_or_b32 v4, v5, s10, v4
	v_and_b32_e32 v6, 4, v6
	v_and_b32_e32 v7, 24, v7
	v_and_b32_e32 v2, 32, v2
	v_bfe_i32 v1, v1, 0, 16
	v_or3_b32 v4, v4, v6, v7
	v_add_lshl_u32 v1, v2, v1, 1
	s_load_dwordx2 s[0:1], s[64:65], 0xc0
	v_lshl_add_u32 v128, v4, 9, v1
	v_lshl_add_u32 v130, v5, 9, v1
	v_ashrrev_i32_e32 v1, 31, v0
	v_lshrrev_b32_e32 v1, 22, v1
	v_add_u32_e32 v1, v0, v1
	v_ashrrev_i32_e32 v1, 10, v1
	s_ashr_i32 s36, s7, 31
	s_ashr_i32 s37, s40, 31
	v_mul_i32_i24_e32 v2, 0x400, v1
	s_waitcnt lgkmcnt(0)
	s_add_u32 s38, s0, 0x1f800000
	v_sub_u32_e32 v0, v0, v2
	s_addc_u32 s39, s1, 0
	v_lshrrev_b32_e32 v2, 4, v0
	s_add_u32 s41, s0, 0x1f500000
	v_bitop3_b32 v0, v2, v0, 32 bitop3:0x6c
	s_addc_u32 s42, s1, 0
	s_lshr_b32 s8, s37, 29
	v_ashrrev_i32_e32 v2, 31, v0
	s_add_i32 s8, s40, s8
	v_lshrrev_b32_e32 v2, 26, v2
	s_ashr_i32 s9, s8, 3
	s_and_b32 s8, s8, -8
	v_add_u32_e32 v2, v0, v2
	v_lshlrev_b32_e32 v5, 3, v1
	s_sub_i32 s8, s40, s8
	v_ashrrev_i32_e32 v4, 6, v2
	v_and_b32_e32 v5, -16, v5
	s_cmp_lt_i32 s8, 0
	v_add_u32_e32 v5, v4, v5
	v_and_b32_e32 v4, 3, v4
	s_movk_i32 s43, 0x49
	v_and_or_b32 v4, v5, s10, v4
	s_cselect_b32 s10, s43, 0x48
	s_mul_i32 s8, s8, s10
	s_add_i32 s8, s8, s9
	s_ashr_i32 s9, s8, 31
	s_lshr_b32 s9, s9, 25
	s_add_i32 s9, s8, s9
	s_ashr_i32 s10, s9, 7
	v_and_b32_e32 v2, 0xc0, v2
	s_lshl_b32 s10, s10, 3
	v_sub_u32_e32 v0, v0, v2
	s_sub_i32 s11, 36, s10
	v_lshlrev_b32_e32 v1, 5, v1
	v_ashrrev_i16_sdwa v0, v3, sext(v0) dst_sel:DWORD dst_unused:UNUSED_PAD src0_sel:DWORD src1_sel:BYTE_0
	s_min_u32 s11, s11, 8
	s_and_b32 s9, s9, 0xffffff80
	v_and_b32_e32 v1, 32, v1
	v_bfe_i32 v0, v0, 0, 16
	s_sub_i32 s15, s8, s9
	v_cvt_f32_ubyte0_e32 v2, s11
	v_add_lshl_u32 v0, v1, v0, 1
	v_cvt_f32_i32_e32 v1, s15
	v_rcp_iflag_f32_e32 v3, v2
	v_lshrrev_b32_e32 v6, 2, v5
	v_lshlrev_b32_e32 v7, 1, v5
	v_and_b32_e32 v6, 4, v6
	v_and_b32_e32 v7, 24, v7
	v_or3_b32 v4, v4, v6, v7
	v_lshl_add_u32 v132, v4, 9, v0
	v_lshl_add_u32 v134, v5, 9, v0
	v_mul_f32_e32 v0, v1, v3
	v_trunc_f32_e32 v0, v0
	v_fma_f32 v1, -v0, v2, v1
	v_cvt_i32_f32_e32 v0, v0
	s_ashr_i32 s8, s15, 30
	s_or_b32 s14, s8, 1
	v_cmp_ge_f32_e64 s[8:9], |v1|, v2
	s_and_b64 s[8:9], s[8:9], exec
	s_cselect_b32 s8, s14, 0
	v_readfirstlane_b32 s9, v0
	s_add_i32 s14, s9, s8
	s_mul_i32 s8, s14, s11
	s_sub_i32 s8, s15, s8
	s_sext_i32_i8 s8, s8
	s_add_i32 s24, s10, s8
	s_ashr_i32 s25, s24, 31
	s_bfe_i64 s[10:11], s[14:15], 0x80000
	s_lshl_b64 s[8:9], s[24:25], 17
	s_lshl_b64 s[10:11], s[10:11], 17
	s_add_u32 s26, s41, s10
	s_addc_u32 s27, s42, s11
	s_add_i32 s25, s93, 0
	s_add_i32 m0, s25, 0x10000
	v_mov_b32_e32 v133, 0
	global_load_lds_dwordx4 v132, s[26:27]
	s_add_i32 m0, s25, 0x12000
	s_add_u32 s28, s38, s8
	s_addc_u32 s29, s39, s9
	s_add_u32 s8, s26, 0x10000
	global_load_lds_dwordx4 v128, s[26:27]
	s_addc_u32 s9, s27, 0
	s_add_i32 m0, s25, 0x14000
	s_add_i32 s44, s25, 0x2000
	global_load_lds_dwordx4 v132, s[8:9]
	s_add_i32 m0, s25, 0x16000
	v_readlane_b32 s4, v250, 21
	global_load_lds_dwordx4 v128, s[8:9]
	s_mov_b32 m0, s25
	s_add_u32 s8, s28, 0x10000
	global_load_lds_dwordx4 v134, s[28:29]
	s_mov_b32 m0, s44
	s_addc_u32 s9, s29, 0
	s_add_i32 s45, s25, 0x4000
	global_load_lds_dwordx4 v130, s[28:29]
	s_mov_b32 m0, s45
	s_add_i32 s46, s25, 0x6000
	global_load_lds_dwordx4 v134, s[8:9]
	s_mov_b32 m0, s46
	v_mov_b32_e32 v129, v133
	global_load_lds_dwordx4 v130, s[8:9]
	v_mov_b32_e32 v135, v133
	v_mov_b32_e32 v131, v133
	v_readlane_b32 s5, v250, 22
	s_mov_b32 s47, 0
	v_lshl_add_u64 v[6:7], s[26:27], 0, v[132:133]
	v_lshl_add_u64 v[4:5], s[26:27], 0, v[128:129]
	v_lshl_add_u64 v[0:1], s[28:29], 0, v[134:135]
	s_and_b64 vcc, exec, s[4:5]
	v_lshl_add_u64 v[2:3], s[28:29], 0, v[130:131]
	s_cbranch_vccnz .LBB0_965
	s_barrier

.LBB0_977:
	s_waitcnt vmcnt(0)
	s_barrier
	s_mov_b32 s40, s99
